# attention main loop: one workgroup barrier per iteration (2 half-steps): K/V tiles in two LDS buffer sets by (tile>>1)&1, K loaded two tiles ahead (preheader adds tile 2), V one earlier, LDS read base
# speedup vs baseline: 1.0053x; 1.0053x over previous
; #define SBAR() __builtin_amdgcn_sched_barrier(0)
; #define SLOAD_H(Kp, Vp, k0) do { S.st_v0 = load8(ROW(Vp, k0, sr)); S.st_v1 = load8(ROW(Vp, k0, 32 + sr));              \
;                          S.st_k0 = load8(ROW(Kp, k0, sr)); S.st_k1 = load8(ROW(Kp, k0, 32 + sr)); } while (0)
; #define SWRITE_HV(bf) do { *(bf16x8*)(V_lds + (bf) * SHM_V + vst0) = S.st_v0; *(bf16x8*)(V_lds + (bf) * SHM_V + vst1) = S.st_v1; } while (0)
; template <int KB>
; __device__ __forceinline__ void qkt(f32x16& p0, f32x16& p1, const char* K_lds, int r32, int hi, const bf16x8* qr) {
;     p0 = f32x16{}; p1 = f32x16{};
;     const char* kb[4];
; #pragma unroll
;     for (int dd = 0; dd < 4; ++dd) kb[dd] = K_lds + KB * SHM_K + KSWZ(r32, (dd * 16 + hi * 8) * 2);
; #pragma unroll
;     for (int d0 = 0; d0 < 8; ++d0) { const char* a = kb[d0 & 3] + (d0 >> 2) * 128;
;         bf16x8 b0 = *reinterpret_cast<const bf16x8*>(a);
;         bf16x8 b1 = *reinterpret_cast<const bf16x8*>(a + 32 * 256);
;         p0 = __builtin_amdgcn_mfma_f32_32x32x16_bf16(b0, qr[d0], p0, 0, 0, 0);
;         p1 = __builtin_amdgcn_mfma_f32_32x32x16_bf16(b1, qr[d0], p1, 0, 0, 0); }
; }
; __device__ __forceinline__ void moba_block(const BlockRef& cur, const BlockRef& nxt, char* lds, Seam& S) {
;     ...
;     SWRITE_HV(0); SBAR();
;     if (NT > 1) { SLOAD_H(Kh, Vh, KBASE(1)); }
;     SBAR(); qkt<0>(pA0, pA1, K_lds, r32, hi, S.qr);
.LBB0_86:
	v_ashrrev_i32_e32 v166, 4, v183
	s_ashr_i32 s0, s3, 1
	v_and_b32_e32 v4, 0xfffff0, v166
	v_lshlrev_b32_e32 v5, 1, v166
	s_and_b32 s94, s0, 0xffffffe0
	v_lshlrev_b32_e32 v50, 2, v182
	v_and_or_b32 v4, v5, 8, v4
	v_lshrrev_b32_e32 v5, 1, v166
	v_and_b32_e32 v6, 3, v166
	v_add_u32_e32 v168, 32, v166
	s_add_i32 s6, s94, s2
	v_sub_u32_e32 v2, v184, v50
	v_and_or_b32 v5, v5, 4, v6
	v_and_b32_e32 v6, 0xfffff0, v168
	v_lshlrev_b32_e32 v7, 1, v168
	v_add_u32_e32 v190, s6, v2
	v_lshlrev_b32_e32 v2, 3, v183
	v_and_or_b32 v6, v7, 8, v6
	v_and_b32_e32 v3, 0x78, v2
	v_lshrrev_b32_e32 v4, 1, v4
	v_bfe_u32 v2, v2, 5, 2
	v_lshrrev_b32_e32 v6, 1, v6
	v_or_b32_e32 v4, v4, v2
	v_lshlrev_b32_e32 v98, 1, v3
	v_or_b32_e32 v2, v6, v2
	v_lshlrev_b32_e32 v4, 9, v4
	v_lshlrev_b32_e32 v5, 6, v5
	v_and_b32_e32 v3, 48, v98
	v_lshlrev_b32_e32 v2, 9, v2
	v_or3_b32 v4, v4, v5, v3
	v_or3_b32 v2, v2, v5, v3
	v_add_u32_e32 v191, 0, v4
	v_add_u32_e32 v192, 0, v2
	ds_write_b128 v191, v[100:103]
	ds_write_b128 v192, v[136:139]
	v_ashrrev_i32_e32 v167, 31, v166
	v_lshlrev_b64 v[2:3], 8, v[166:167]
	s_mov_b64 s[0:1], 0x4000
	v_lshl_add_u64 v[4:5], v[2:3], 0, s[0:1]
	s_mov_b64 s[0:1], 0x6000
	v_lshl_add_u64 v[6:7], s[22:23], 0, v[4:5]
	v_lshl_add_u64 v[2:3], v[2:3], 0, s[0:1]
	v_lshl_add_u64 v[4:5], s[30:31], 0, v[4:5]
	v_lshl_add_u64 v[6:7], v[6:7], 0, v[98:99]
	v_lshl_add_u64 v[8:9], s[22:23], 0, v[2:3]
	v_lshl_add_u64 v[4:5], v[4:5], 0, v[98:99]
	v_lshl_add_u64 v[2:3], s[30:31], 0, v[2:3]
	v_lshl_add_u64 v[8:9], v[8:9], 0, v[98:99]
	global_load_dwordx4 v[34:37], v[6:7], off
	global_load_dwordx4 v[38:41], v[8:9], off
	v_lshl_add_u64 v[2:3], v[2:3], 0, v[98:99]
	global_load_dwordx4 v[42:45], v[4:5], off
	global_load_dwordx4 v[46:49], v[2:3], off
	v_readfirstlane_b32 s32, v0
	s_lshr_b32 s32, s32, 6
	s_lshl_b32 s32, s32, 10
	s_add_i32 s32, s32, 0x8000
	v_lshrrev_b32_e32 v236, 4, v0
	v_and_b32_e32 v237, 7, v236
	v_and_b32_e32 v240, 15, v0
	v_xor_b32_e32 v237, v237, v240
	v_lshlrev_b32_e32 v237, 4, v237
	v_lshlrev_b32_e32 v236, 8, v236
	v_add_u32_e32 v236, 0x8000, v236
	v_add_u32_e32 v240, v236, v237
	v_mov_b32_e32 v241, 0
	v_lshl_add_u64 v[244:245], s[30:31], 0, v[240:241]
	v_add_u32_e32 v240, 0x2000, v240
	v_lshl_add_u64 v[246:247], s[30:31], 0, v[240:241]
	s_add_i32 m0, s32, 0x13400
	s_nop 0
	global_load_lds_dwordx4 v[244:245], off
	s_add_i32 m0, m0, 0x2000
	s_nop 0
	global_load_lds_dwordx4 v[246:247], off
	v_mov_b32_e32 v250, 0x4000
	v_mov_b32_e32 v251, 0
	v_lshl_add_u64 v[244:245], v[244:245], 0, v[250:251]
	v_lshl_add_u64 v[246:247], v[246:247], 0, v[250:251]
	v_lshrrev_b32_e32 v236, 6, v0
	v_bfe_u32 v237, v0, 2, 3
	v_lshrrev_b32_e32 v240, 1, v236
	v_lshlrev_b32_e32 v240, 4, v240
	v_and_b32_e32 v242, 4, v237
	v_lshl_or_b32 v240, v242, 1, v240
	v_and_b32_e32 v242, 1, v236
	v_lshl_or_b32 v240, v242, 2, v240
	v_and_b32_e32 v242, 3, v237
	v_or_b32_e32 v240, v240, v242
	v_lshlrev_b32_e32 v240, 8, v240
	v_bfe_u32 v242, v0, 5, 1
	v_lshl_or_b32 v240, v242, 6, v240
	v_and_b32_e32 v242, 3, v0
	v_lshl_or_b32 v240, v242, 4, v240
	v_add_u32_e32 v240, 0x8000, v240
	v_lshl_add_u64 v[248:249], s[22:23], 0, v[240:241]
	v_lshlrev_b32_e32 v2, 4, v184
	v_and_b32_e32 v56, 0x70, v2
	v_lshlrev_b32_e32 v51, 8, v184
	v_xad_u32 v2, v164, v56, 0
	v_add_u32_e32 v169, v2, v51
	ds_read_b128 v[2:5], v169 offset:32768
	v_or_b32_e32 v6, 32, v164
	v_xad_u32 v6, v6, v56, 0
	v_add_u32_e32 v193, v6, v51
	ds_read_b128 v[52:55], v193 offset:32768
	v_or_b32_e32 v57, 64, v164
	v_xad_u32 v57, v57, v56, 0
	v_add_u32_e32 v194, v57, v51
	s_waitcnt lgkmcnt(1)
	v_mfma_f32_32x32x16_bf16 v[18:33], v[2:5], v[132:135], 0
	ds_read_b128 v[2:5], v169 offset:40960
	v_or_b32_e32 v57, 0x60, v164
	v_xad_u32 v56, v57, v56, 0
	v_add_u32_e32 v195, v56, v51
	s_cmp_gt_i32 s6, 62
	s_waitcnt lgkmcnt(1)
	v_mfma_f32_32x32x16_bf16 v[18:33], v[52:55], v[128:131], v[18:33]
	ds_read_b128 v[52:55], v193 offset:40960
	s_waitcnt lgkmcnt(1)
	v_mfma_f32_32x32x16_bf16 v[2:17], v[2:5], v[132:135], 0
	s_waitcnt lgkmcnt(0)
	v_mfma_f32_32x32x16_bf16 v[2:17], v[52:55], v[128:131], v[2:17]
	ds_read_b128 v[52:55], v194 offset:32768
	s_waitcnt lgkmcnt(0)
	v_mfma_f32_32x32x16_bf16 v[18:33], v[52:55], v[124:127], v[18:33]
	ds_read_b128 v[52:55], v194 offset:40960
	s_waitcnt lgkmcnt(0)
	v_mfma_f32_32x32x16_bf16 v[2:17], v[52:55], v[124:127], v[2:17]
	ds_read_b128 v[52:55], v195 offset:32768
	s_waitcnt lgkmcnt(0)
	v_mfma_f32_32x32x16_bf16 v[18:33], v[52:55], v[120:123], v[18:33]
	ds_read_b128 v[52:55], v195 offset:40960
	s_waitcnt lgkmcnt(0)
	v_mfma_f32_32x32x16_bf16 v[2:17], v[52:55], v[120:123], v[2:17]
	ds_read_b128 v[52:55], v169 offset:32896
	s_waitcnt lgkmcnt(0)
	v_mfma_f32_32x32x16_bf16 v[18:33], v[52:55], v[116:119], v[18:33]
	ds_read_b128 v[52:55], v169 offset:41088
	s_waitcnt lgkmcnt(0)
	v_mfma_f32_32x32x16_bf16 v[2:17], v[52:55], v[116:119], v[2:17]
	ds_read_b128 v[52:55], v193 offset:32896
	s_waitcnt lgkmcnt(0)
	v_mfma_f32_32x32x16_bf16 v[18:33], v[52:55], v[112:115], v[18:33]
	ds_read_b128 v[52:55], v193 offset:41088
	s_waitcnt lgkmcnt(0)
	v_mfma_f32_32x32x16_bf16 v[2:17], v[52:55], v[112:115], v[2:17]
	ds_read_b128 v[52:55], v194 offset:32896
	s_waitcnt lgkmcnt(0)
	v_mfma_f32_32x32x16_bf16 v[18:33], v[52:55], v[108:111], v[18:33]
	ds_read_b128 v[52:55], v194 offset:41088
	s_waitcnt lgkmcnt(0)
	v_mfma_f32_32x32x16_bf16 v[2:17], v[52:55], v[108:111], v[2:17]
	ds_read_b128 v[52:55], v195 offset:32896
	s_waitcnt lgkmcnt(0)
	v_mfma_f32_32x32x16_bf16 v[18:33], v[52:55], v[104:107], v[18:33]
	ds_read_b128 v[52:55], v195 offset:41088
	s_waitcnt lgkmcnt(0)
	v_mfma_f32_32x32x16_bf16 v[2:17], v[52:55], v[104:107], v[2:17]
	s_cbranch_scc1 .LBB0_88
; __device__ __forceinline__ void mask_tile(f32x16& p0, f32x16& p1, int dq, unsigned W) {
;     const float NEG = -__builtin_inff();
; #pragma unroll
;     for (int r = 0; r < 16; ++r) {
;         const int c = (r & 3) + 8 * (r >> 2);
;         if ((unsigned)(dq - c) >= W) p0[r] = NEG;
;         if ((unsigned)(dq - c - 32) >= W) p1[r] = NEG;
;     }
; }
; __device__ __forceinline__ void partialSM(f32x16& p0, f32x16& p1, float& m_reg, float& mn, float& alpha, bool rs) {
;     float pmax = p0[0]; for (int r = 1; r < 16; ++r) pmax = fmaxf(pmax, p0[r]); for (int r = 0; r < 16; ++r) pmax = fmaxf(pmax, p1[r]);
;     if (!rs) pmax = -__builtin_inff();
;     { auto rr = __builtin_amdgcn_permlane32_swap(__float_as_uint(pmax), __float_as_uint(pmax), false, false);
;       pmax = fmaxf(__uint_as_float(rr[0]), __uint_as_float(rr[1])); }
;     constexpr float C2 = 1.4426950408889634f * SCALE;
;     if (__builtin_expect(__all((pmax - m_reg) * SCALE <= THR), 1)) { mn = m_reg; alpha = 1.f; }
;     else { mn = fmaxf(m_reg, pmax); alpha = __builtin_amdgcn_exp2f((m_reg - mn) * C2); m_reg = mn; }
;     const float mnL = rs ? -mn * C2 : -__builtin_inff();
;     for (int r = 0; r < 16; ++r) p0[r] = fmaf(p0[r], C2, mnL); for (int r = 0; r < 16; ++r) p1[r] = fmaf(p1[r], C2, mnL);
;     for (int r = 0; r < 16; ++r) p0[r] = __builtin_amdgcn_exp2f(p0[r]);
; }
	v_cmp_gt_u32_e32 vcc, 2.0, v190
	v_add_u32_e32 v51, 0xbfffffe0, v190
	s_nop 5
	v_cndmask_b32_e32 v18, v220, v18, vcc
	v_cmp_lt_u32_e32 vcc, s33, v51
	v_add_u32_e32 v51, 0xbfffffff, v190
	s_nop 0
	v_cndmask_b32_e32 v2, v220, v2, vcc
	v_cmp_lt_u32_e32 vcc, s33, v51
	v_add_u32_e32 v51, 0xbfffffdf, v190
	s_nop 0
	v_cndmask_b32_e32 v19, v220, v19, vcc
	v_cmp_lt_u32_e32 vcc, s33, v51
	v_add_u32_e32 v51, 0xbffffffe, v190
	s_nop 0
	v_cndmask_b32_e32 v3, v220, v3, vcc
	v_cmp_lt_u32_e32 vcc, s33, v51
	v_add_u32_e32 v51, 0xbfffffde, v190
	s_nop 0
	v_cndmask_b32_e32 v20, v220, v20, vcc
	v_cmp_lt_u32_e32 vcc, s33, v51
	v_add_u32_e32 v51, 0xbffffffd, v190
	s_nop 0
	v_cndmask_b32_e32 v4, v220, v4, vcc
	v_cmp_lt_u32_e32 vcc, s33, v51
	v_add_u32_e32 v51, 0xbfffffdd, v190
	s_nop 0
	v_cndmask_b32_e32 v21, v220, v21, vcc
	v_cmp_lt_u32_e32 vcc, s33, v51
	v_add_u32_e32 v51, 0xbffffff8, v190
	s_nop 0
	v_cndmask_b32_e32 v5, v220, v5, vcc
	v_cmp_lt_u32_e32 vcc, s33, v51
	v_add_u32_e32 v51, 0xbfffffd8, v190
	s_nop 0
	v_cndmask_b32_e32 v22, v220, v22, vcc
	v_cmp_lt_u32_e32 vcc, s33, v51
	v_add_u32_e32 v51, 0xbffffff7, v190
	s_nop 0
	v_cndmask_b32_e32 v6, v220, v6, vcc
	v_cmp_lt_u32_e32 vcc, s33, v51
	v_add_u32_e32 v51, 0xbfffffd7, v190
	s_nop 0
	v_cndmask_b32_e32 v23, v220, v23, vcc
	v_cmp_lt_u32_e32 vcc, s33, v51
	v_add_u32_e32 v51, 0xbffffff6, v190
	s_nop 0
	v_cndmask_b32_e32 v7, v220, v7, vcc
	v_cmp_lt_u32_e32 vcc, s33, v51
	v_add_u32_e32 v51, 0xbfffffd6, v190
	s_nop 0
	v_cndmask_b32_e32 v24, v220, v24, vcc
	v_cmp_lt_u32_e32 vcc, s33, v51
	v_add_u32_e32 v51, 0xbffffff5, v190
	s_nop 0
	v_cndmask_b32_e32 v8, v220, v8, vcc
	v_cmp_lt_u32_e32 vcc, s33, v51
	v_add_u32_e32 v51, 0xbfffffd5, v190
	s_nop 0
	v_cndmask_b32_e32 v25, v220, v25, vcc
	v_cmp_lt_u32_e32 vcc, s33, v51
	v_add_u32_e32 v51, 0xbffffff0, v190
	s_nop 0
	v_cndmask_b32_e32 v9, v220, v9, vcc
	v_cmp_lt_u32_e32 vcc, s33, v51
	v_add_u32_e32 v51, 0xbfffffd0, v190
	s_nop 0
	v_cndmask_b32_e32 v26, v220, v26, vcc
	v_cmp_lt_u32_e32 vcc, s33, v51
	v_add_u32_e32 v51, 0xbfffffef, v190
	s_nop 0
	v_cndmask_b32_e32 v10, v220, v10, vcc
	v_cmp_lt_u32_e32 vcc, s33, v51
	v_add_u32_e32 v51, 0xbfffffcf, v190
	s_nop 0
	v_cndmask_b32_e32 v27, v220, v27, vcc
	v_cmp_lt_u32_e32 vcc, s33, v51
	v_add_u32_e32 v51, 0xbfffffee, v190
	s_nop 0
	v_cndmask_b32_e32 v11, v220, v11, vcc
	v_cmp_lt_u32_e32 vcc, s33, v51
	v_add_u32_e32 v51, 0xbfffffce, v190
	s_nop 0
	v_cndmask_b32_e32 v28, v220, v28, vcc
	v_cmp_lt_u32_e32 vcc, s33, v51
	v_add_u32_e32 v51, 0xbfffffed, v190
	s_nop 0
	v_cndmask_b32_e32 v12, v220, v12, vcc
	v_cmp_lt_u32_e32 vcc, s33, v51
	v_add_u32_e32 v51, 0xbfffffcd, v190
	s_nop 0
	v_cndmask_b32_e32 v29, v220, v29, vcc
	v_cmp_lt_u32_e32 vcc, s33, v51
	v_add_u32_e32 v51, 0xbfffffe8, v190
	s_nop 0
	v_cndmask_b32_e32 v13, v220, v13, vcc
	v_cmp_lt_u32_e32 vcc, s33, v51
	v_add_u32_e32 v51, 0xbfffffc8, v190
	s_nop 0
	v_cndmask_b32_e32 v30, v220, v30, vcc
	v_cmp_lt_u32_e32 vcc, s33, v51
	v_add_u32_e32 v51, 0xbfffffe7, v190
	s_nop 0
	v_cndmask_b32_e32 v14, v220, v14, vcc
	v_cmp_lt_u32_e32 vcc, s33, v51
	v_add_u32_e32 v51, 0xbfffffc7, v190
	s_nop 0
	v_cndmask_b32_e32 v31, v220, v31, vcc
	v_cmp_lt_u32_e32 vcc, s33, v51
	v_add_u32_e32 v51, 0xbfffffe6, v190
	s_nop 0
	v_cndmask_b32_e32 v15, v220, v15, vcc
	v_cmp_lt_u32_e32 vcc, s33, v51
	v_add_u32_e32 v51, 0xbfffffc6, v190
	s_nop 0
	v_cndmask_b32_e32 v32, v220, v32, vcc
	v_cmp_lt_u32_e32 vcc, s33, v51
	v_add_u32_e32 v51, 0xbfffffe5, v190
	s_nop 0
	v_cndmask_b32_e32 v16, v220, v16, vcc
	v_cmp_lt_u32_e32 vcc, s33, v51
	v_add_u32_e32 v51, 0xbfffffc5, v190
	s_nop 0
	v_cndmask_b32_e32 v33, v220, v33, vcc
	v_cmp_lt_u32_e32 vcc, s33, v51
	s_nop 1
	v_cndmask_b32_e32 v17, v220, v17, vcc
.LBB0_88:
	s_and_b32 s0, s3, 0x3fffffc0
	v_and_b32_e32 v51, 63, v183
	s_lshl_b32 s0, s0, 2
	s_lshl_b32 s2, s44, 2
	s_add_i32 s0, s0, 0
	v_lshlrev_b32_e32 v52, 8, v166
	v_and_b32_e32 v53, 0x70, v183
	v_lshlrev_b32_e32 v54, 4, v51
	s_xor_b64 s[10:11], s[10:11], -1
	s_add_i32 s2, s2, 4
	s_add_i32 s7, s0, 0x10000
	v_bitop3_b32 v53, v98, v52, v53 bitop3:0xde
	v_lshlrev_b32_e32 v52, 3, v51
	v_and_b32_e32 v54, 0xc0, v54
	v_lshlrev_b32_e32 v55, 1, v51
	v_and_or_b32 v54, v52, 24, v54
	v_and_b32_e32 v55, 32, v55
	v_and_b32_e32 v52, 0x100, v52
	s_cmp_lg_u32 0, -1
	v_or3_b32 v52, v54, v55, v52
	s_cselect_b32 s0, 0, 0
	v_add_u32_e32 v185, s0, v52
	v_and_b32_e32 v52, 1, v165
	v_cmp_eq_u32_e32 vcc, 1, v52
	v_max_f32_e32 v52, v19, v19
	v_max_f32_e32 v54, v18, v18
	v_max_f32_e32 v52, v54, v52
	v_max3_f32 v52, v52, v20, v21
	v_max3_f32 v52, v52, v22, v23
	v_max3_f32 v52, v52, v24, v25
	v_max3_f32 v52, v52, v26, v27
	v_max3_f32 v52, v52, v28, v29
	v_max3_f32 v52, v52, v30, v31
	v_max3_f32 v52, v52, v32, v33
	v_max3_f32 v52, v52, v2, v3
	v_max3_f32 v52, v52, v4, v5
	v_max3_f32 v52, v52, v6, v7
	v_max3_f32 v52, v52, v8, v9
	v_max3_f32 v52, v52, v10, v11
	s_cmp_lt_i32 s44, 1
	v_max3_f32 v52, v52, v12, v13
	s_cselect_b64 s[0:1], -1, 0
	v_max3_f32 v52, v52, v14, v15
	v_max3_f32 v52, v52, v16, v17
	s_or_b64 vcc, s[0:1], vcc
	v_cndmask_b32_e32 v52, v220, v52, vcc
	v_mov_b32_e32 v54, v52
	s_nop 1
	v_permlane32_swap_b32_e32 v52, v54
	v_max_f32_e32 v54, v54, v54
	v_max_f32_e32 v52, v52, v52
	v_max_f32_e32 v52, v52, v54
	v_add_f32_e32 v54, 0x7149f2ca, v52
	v_mul_f32_e32 v54, 0x3db504f3, v54
	v_max_f32_e32 v52, 0xf149f2ca, v52
	v_cmp_ge_f32_e64 s[38:39], s91, v54
	v_sub_f32_e32 v54, 0xf149f2ca, v52
	v_mul_f32_e32 v54, 0x3e0293ee, v54
	s_cmp_eq_u64 s[38:39], exec
	v_exp_f32_e32 v54, v54
	s_cselect_b64 s[38:39], -1, 0
	v_mov_b32_e32 v55, 0xf149f2ca
	v_cndmask_b32_e64 v198, v52, v55, s[38:39]
	v_mul_f32_e32 v52, 0xbe0293ee, v198
	v_cndmask_b32_e32 v52, v220, v52, vcc
	v_cndmask_b32_e64 v196, v54, 1.0, s[38:39]
	v_mov_b32_e32 v54, v52
	v_fmamk_f32 v18, v18, 0x3e0293ee, v52
	v_fmamk_f32 v19, v19, 0x3e0293ee, v52
	v_fmamk_f32 v20, v20, 0x3e0293ee, v52
	v_fmamk_f32 v21, v21, 0x3e0293ee, v52
	v_fmamk_f32 v22, v22, 0x3e0293ee, v52
	v_fmamk_f32 v23, v23, 0x3e0293ee, v52
	v_fmamk_f32 v24, v24, 0x3e0293ee, v52
	v_fmamk_f32 v25, v25, 0x3e0293ee, v52
	v_fmamk_f32 v26, v26, 0x3e0293ee, v52
	v_fmamk_f32 v27, v27, 0x3e0293ee, v52
	v_fmamk_f32 v28, v28, 0x3e0293ee, v52
	v_fmamk_f32 v29, v29, 0x3e0293ee, v52
	v_fmamk_f32 v30, v30, 0x3e0293ee, v52
	v_fmamk_f32 v31, v31, 0x3e0293ee, v52
	v_fmamk_f32 v32, v32, 0x3e0293ee, v52
	v_fmac_f32_e32 v54, 0x3e0293ee, v33
	s_add_i32 s0, s6, 0xbfffff45
	v_pk_fma_f32 v[178:179], v[2:3], s[20:21], v[52:53] op_sel_hi:[1,0,0]
	v_exp_f32_e32 v231, v18
	v_exp_f32_e32 v233, v19
	v_exp_f32_e32 v229, v20
	v_exp_f32_e32 v232, v21
	v_exp_f32_e32 v228, v22
	v_exp_f32_e32 v230, v23
	v_exp_f32_e32 v226, v24
	v_exp_f32_e32 v227, v25
	v_exp_f32_e32 v223, v26
	v_exp_f32_e32 v225, v27
	v_exp_f32_e32 v209, v28
	v_exp_f32_e32 v224, v29
	v_exp_f32_e32 v206, v30
	v_exp_f32_e32 v208, v31
	v_exp_f32_e32 v205, v32
	v_exp_f32_e32 v207, v54
	v_add_u32_e32 v2, s0, v184
	s_waitcnt vmcnt(0)
; #define SBAR() __builtin_amdgcn_sched_barrier(0)
; #define VMW() asm volatile("s_waitcnt vmcnt(0)" ::: "memory")
; #define SWRITE_H(bf) do { SWRITE_HV(bf); SWRITE_HK(bf); } while (0)
; #define MASKT(P0_, P1_, t) do { const int kb_ = KBASE(t); if (kb_ + KVBLK - 1 > qlo) mask_tile(P0_, P1_, qm - kb_, (unsigned)W); } while (0)
; __device__ __forceinline__ void finishSM(f32x16& p0, f32x16& p1, float alpha, float& l_reg, bf16x8& pa0, bf16x8& pa1, bf16x8& pa2, bf16x8& pa3) {
;     for (int r = 0; r < 16; ++r) p1[r] = __builtin_amdgcn_exp2f(p1[r]);
;     float ps = 0; for (int r = 0; r < 16; ++r) ps += p0[r]; for (int r = 0; r < 16; ++r) ps += p1[r];
;     { auto rr = __builtin_amdgcn_permlane32_swap(__float_as_uint(ps), __float_as_uint(ps), false, false);
;       ps = __uint_as_float(rr[0]) + __uint_as_float(rr[1]); }
;     l_reg = l_reg * alpha + ps;
;     ...
;     PK4(p0, 0, pa0); PK4(p0, 8, pa1); PK4(p1, 0, pa2); PK4(p1, 8, pa3);
;     ...
; }
; __device__ __forceinline__ void moba_block(const BlockRef& cur, const BlockRef& nxt, char* lds, Seam& S) {
;     ...
;     SBAR(); qkt<0>(pA0, pA1, K_lds, r32, hi, S.qr);
;     MASKT(pA0, pA1, 0); partialSM(pA0, pA1, m_reg, mnA, alA, RSEL(0));
;     if (NT > 1) { VMW(); SWRITE_H(1); }
;     __syncthreads();
	v_add_u32_e32 v188, 0, v53
	v_cmp_gt_u32_e64 s[38:39], 32, v51
	v_lshl_add_u32 v186, v50, 2, s7
	v_sub_u32_e32 v197, v2, v50
	v_mov_b32_e32 v50, v99
	v_mov_b32_e32 v51, v99
	v_pk_fma_f32 v[154:155], v[16:17], s[20:21], v[52:53] op_sel_hi:[1,0,0]
	v_pk_fma_f32 v[160:161], v[14:15], s[20:21], v[52:53] op_sel_hi:[1,0,0]
	v_pk_fma_f32 v[180:181], v[12:13], s[20:21], v[52:53] op_sel_hi:[1,0,0]
	v_pk_fma_f32 v[152:153], v[10:11], s[20:21], v[52:53] op_sel_hi:[1,0,0]
	v_pk_fma_f32 v[156:157], v[8:9], s[20:21], v[52:53] op_sel_hi:[1,0,0]
	v_pk_fma_f32 v[158:159], v[6:7], s[20:21], v[52:53] op_sel_hi:[1,0,0]
	v_pk_fma_f32 v[162:163], v[4:5], s[20:21], v[52:53] op_sel_hi:[1,0,0]
	s_waitcnt vmcnt(3)
	ds_write_b128 v191, v[34:37] offset:16384
	s_waitcnt vmcnt(2)
	ds_write_b128 v192, v[38:41] offset:16384
	s_waitcnt vmcnt(1)
	ds_write_b128 v188, v[42:45] offset:49152
	s_waitcnt vmcnt(0)
	ds_write_b128 v188, v[46:49] offset:57344
	v_mov_b32_e32 v52, v99
	v_mov_b32_e32 v53, v99
	v_mov_b32_e32 v54, v99
	v_mov_b32_e32 v55, v99
	v_mov_b32_e32 v56, v99
	v_mov_b32_e32 v57, v99
	v_mov_b32_e32 v58, v99
	v_mov_b32_e32 v59, v99
	v_mov_b32_e32 v60, v99
	v_mov_b32_e32 v61, v99
	v_mov_b32_e32 v62, v99
	v_mov_b32_e32 v63, v99
	v_mov_b32_e32 v64, v99
	v_mov_b32_e32 v65, v99
	v_mov_b64_e32 v[34:35], v[50:51]
	v_mov_b64_e32 v[18:19], v[50:51]
	v_mov_b64_e32 v[2:3], v[50:51]
	s_mov_b32 s3, 3
	v_lshl_add_u64 v[170:171], s[22:23], 0, v[98:99]
	v_lshl_add_u64 v[176:177], s[30:31], 0, v[98:99]
	v_lshl_add_u32 v187, v184, 2, s7
	v_mov_b32_e32 v189, 0
	s_movk_i32 s7, 0x7f
	v_mov_b64_e32 v[36:37], v[52:53]
	v_mov_b64_e32 v[38:39], v[54:55]
	v_mov_b64_e32 v[40:41], v[56:57]
	v_mov_b64_e32 v[42:43], v[58:59]
	v_mov_b64_e32 v[44:45], v[60:61]
	v_mov_b64_e32 v[46:47], v[62:63]
	v_mov_b64_e32 v[48:49], v[64:65]
	v_mov_b64_e32 v[20:21], v[52:53]
	v_mov_b64_e32 v[22:23], v[54:55]
	v_mov_b64_e32 v[24:25], v[56:57]
	v_mov_b64_e32 v[26:27], v[58:59]
	v_mov_b64_e32 v[28:29], v[60:61]
	v_mov_b64_e32 v[30:31], v[62:63]
	v_mov_b64_e32 v[32:33], v[64:65]
	v_mov_b64_e32 v[4:5], v[52:53]
	v_mov_b64_e32 v[6:7], v[54:55]
	v_mov_b64_e32 v[8:9], v[56:57]
	v_mov_b64_e32 v[10:11], v[58:59]
	v_mov_b64_e32 v[12:13], v[60:61]
	v_mov_b64_e32 v[14:15], v[62:63]
	v_mov_b64_e32 v[16:17], v[64:65]
	s_mov_b32 s100, 0x13400
	s_waitcnt lgkmcnt(0)
	s_barrier
.LBB0_89:
	ds_read_b128 v[66:69], v169 offset:49152
	ds_read_b128 v[70:73], v169 offset:57344
	ds_read_b128 v[100:103], v193 offset:49152
	ds_read_b128 v[136:139], v193 offset:57344
	v_add_f32_e32 v148, 0, v231
	v_add_f32_e32 v148, v233, v148
	v_add_f32_e32 v148, v229, v148
	v_add_f32_e32 v148, v232, v148
	v_add_f32_e32 v148, v228, v148
	v_add_f32_e32 v148, v230, v148
	v_add_f32_e32 v148, v226, v148
	v_add_f32_e32 v148, v227, v148
	v_add_f32_e32 v148, v223, v148
	v_add_f32_e32 v148, v225, v148
	v_add_f32_e32 v148, v209, v148
	v_add_f32_e32 v148, v224, v148
	v_add_f32_e32 v148, v206, v148
	v_add_f32_e32 v148, v208, v148
	v_add_f32_e32 v148, v205, v148
	v_add_f32_e32 v148, v207, v148
	v_exp_f32_e32 v140, v152
	v_exp_f32_e32 v141, v153
	v_exp_f32_e32 v142, v180
	v_exp_f32_e32 v143, v181
	s_waitcnt lgkmcnt(3)
	v_mfma_f32_32x32x16_bf16 v[82:97], v[66:69], v[132:135], 0
	v_exp_f32_e32 v144, v160
	v_exp_f32_e32 v145, v161
	v_exp_f32_e32 v146, v154
	v_exp_f32_e32 v147, v155
	s_waitcnt lgkmcnt(2)
	v_mfma_f32_32x32x16_bf16 v[66:81], v[70:73], v[132:135], 0
	v_exp_f32_e32 v178, v178
	v_exp_f32_e32 v179, v179
	v_exp_f32_e32 v162, v162
	v_exp_f32_e32 v163, v163
	s_waitcnt lgkmcnt(1)
	v_mfma_f32_32x32x16_bf16 v[82:97], v[100:103], v[128:131], v[82:97]
	v_add_f32_e32 v148, v178, v148
	v_add_f32_e32 v148, v179, v148
	v_add_f32_e32 v148, v162, v148
	v_exp_f32_e32 v158, v158
	s_waitcnt lgkmcnt(0)
	v_mfma_f32_32x32x16_bf16 v[66:81], v[136:139], v[128:131], v[66:81]
	v_exp_f32_e32 v159, v159
	v_exp_f32_e32 v156, v156
	v_exp_f32_e32 v157, v157
	v_add_f32_e32 v148, v163, v148
	ds_read_b128 v[100:103], v194 offset:49152
	ds_read_b128 v[136:139], v194 offset:57344
	s_waitcnt lgkmcnt(1)
	v_mfma_f32_32x32x16_bf16 v[82:97], v[100:103], v[124:127], v[82:97]
	v_add_f32_e32 v148, v158, v148
	v_add_f32_e32 v148, v159, v148
	v_add_f32_e32 v148, v156, v148
	v_add_f32_e32 v148, v157, v148
	s_waitcnt lgkmcnt(0)
	v_mfma_f32_32x32x16_bf16 v[66:81], v[136:139], v[124:127], v[66:81]
	v_add_f32_e32 v148, v140, v148
	v_add_f32_e32 v148, v141, v148
	v_add_f32_e32 v148, v142, v148
	v_add_f32_e32 v148, v143, v148
	ds_read_b128 v[100:103], v195 offset:49152
	ds_read_b128 v[136:139], v195 offset:57344
	s_waitcnt lgkmcnt(1)
	v_mfma_f32_32x32x16_bf16 v[82:97], v[100:103], v[120:123], v[82:97]
	v_add_f32_e32 v148, v144, v148
	v_add_f32_e32 v148, v145, v148
	v_add_f32_e32 v148, v146, v148
	v_add_f32_e32 v199, v147, v148
	s_waitcnt lgkmcnt(0)
	v_mfma_f32_32x32x16_bf16 v[66:81], v[136:139], v[120:123], v[66:81]
	v_mov_b32_e32 v200, v199
	s_nop 1
	v_permlane32_swap_b32_e32 v199, v200
	v_cvt_pk_bf16_f32 v148, v231, v233
	v_cvt_pk_bf16_f32 v149, v229, v232
	v_cvt_pk_bf16_f32 v150, v228, v230
	ds_read_b128 v[100:103], v169 offset:49280
	ds_read_b128 v[136:139], v169 offset:57472
	s_waitcnt lgkmcnt(1)
	v_mfma_f32_32x32x16_bf16 v[82:97], v[100:103], v[116:119], v[82:97]
	v_cvt_pk_bf16_f32 v151, v226, v227
	v_cvt_pk_bf16_f32 v152, v223, v225
	v_cvt_pk_bf16_f32 v153, v209, v224
	s_waitcnt lgkmcnt(0)
	v_mfma_f32_32x32x16_bf16 v[66:81], v[136:139], v[116:119], v[66:81]
	v_cvt_pk_bf16_f32 v154, v206, v208
	v_cvt_pk_bf16_f32 v155, v205, v207
	v_cvt_pk_bf16_f32 v158, v158, v159
	ds_read_b128 v[100:103], v193 offset:49280
	ds_read_b128 v[136:139], v193 offset:57472
	s_waitcnt lgkmcnt(1)
; template <int KB>
; __device__ __forceinline__ void qkt(f32x16& p0, f32x16& p1, const char* K_lds, int r32, int hi, const bf16x8* qr) {
;     p0 = f32x16{}; p1 = f32x16{};
;     const char* kb[4];
; #pragma unroll
;     for (int dd = 0; dd < 4; ++dd) kb[dd] = K_lds + KB * SHM_K + KSWZ(r32, (dd * 16 + hi * 8) * 2);
; #pragma unroll
;     for (int d0 = 0; d0 < 8; ++d0) { const char* a = kb[d0 & 3] + (d0 >> 2) * 128;
;         bf16x8 b0 = *reinterpret_cast<const bf16x8*>(a);
;         bf16x8 b1 = *reinterpret_cast<const bf16x8*>(a + 32 * 256);
;         p0 = __builtin_amdgcn_mfma_f32_32x32x16_bf16(b0, qr[d0], p0, 0, 0, 0);
;         p1 = __builtin_amdgcn_mfma_f32_32x32x16_bf16(b1, qr[d0], p1, 0, 0, 0); }
; }
; template <int VB>
; __device__ __forceinline__ void pv_tile(f32x16* o, int vb0, bf16x8 pa0, bf16x8 pa1, bf16x8 pa2, bf16x8 pa3) {
;     ...
;     PV_D0(0); PV_D0(1); PV_D0(2); PV_D0(3);
;     ...
; }
	v_mfma_f32_32x32x16_bf16 v[82:97], v[100:103], v[112:115], v[82:97]
	v_cvt_pk_bf16_f32 v159, v156, v157
	v_cvt_pk_bf16_f32 v156, v178, v179
	v_cvt_pk_bf16_f32 v157, v162, v163
	s_waitcnt lgkmcnt(0)
	v_mfma_f32_32x32x16_bf16 v[66:81], v[136:139], v[112:115], v[66:81]
	v_cvt_pk_bf16_f32 v160, v140, v141
	v_cvt_pk_bf16_f32 v161, v142, v143
	v_cvt_pk_bf16_f32 v162, v144, v145
	ds_read_b128 v[100:103], v194 offset:49280
	ds_read_b128 v[136:139], v194 offset:57472
	s_waitcnt lgkmcnt(1)
	v_mfma_f32_32x32x16_bf16 v[82:97], v[100:103], v[108:111], v[82:97]
	v_cvt_pk_bf16_f32 v163, v146, v147
	s_nop 0
	v_permlane32_swap_b32_e32 v148, v150
	v_permlane32_swap_b32_e32 v149, v151
	s_waitcnt lgkmcnt(0)
	v_mfma_f32_32x32x16_bf16 v[66:81], v[136:139], v[108:111], v[66:81]
	v_permlane32_swap_b32_e32 v152, v154
	v_permlane32_swap_b32_e32 v153, v155
	v_permlane32_swap_b32_e32 v156, v158
	ds_read_b128 v[100:103], v195 offset:49280
	ds_read_b128 v[136:139], v195 offset:57472
	ds_read_b64_tr_b16 v[172:173], v185 offset:0
	ds_read_b64_tr_b16 v[174:175], v185 offset:0x800
	ds_read_b64_tr_b16 v[202:203], v185 offset:0x1000
	ds_read_b64_tr_b16 v[204:205], v185 offset:0x1800
	ds_read_b64_tr_b16 v[206:207], v185 offset:0x2000
	ds_read_b64_tr_b16 v[208:209], v185 offset:0x2800
	ds_read_b64_tr_b16 v[224:225], v185 offset:0x3000
	ds_read_b64_tr_b16 v[226:227], v185 offset:0x3800
	s_waitcnt lgkmcnt(9)
	v_mfma_f32_32x32x16_bf16 v[82:97], v[100:103], v[104:107], v[82:97]
	v_permlane32_swap_b32_e32 v157, v159
	v_permlane32_swap_b32_e32 v160, v162
	v_permlane32_swap_b32_e32 v161, v163
	s_waitcnt lgkmcnt(8)
	v_mfma_f32_32x32x16_bf16 v[66:81], v[136:139], v[104:107], v[66:81]
	v_add_u32_e32 v169, s100, v169
	v_add_u32_e32 v193, s100, v193
	v_add_u32_e32 v194, s100, v194
	v_add_u32_e32 v195, s100, v195
	s_sub_i32 s100, 0, s100
	s_sub_i32 m0, 0, s100
	s_max_i32 m0, m0, 0
	s_add_i32 m0, m0, s32
	s_add_i32 m0, m0, 0x4000
	s_nop 0
	global_load_lds_dwordx4 v[244:245], off
	s_add_i32 m0, m0, 0x2000
	s_nop 0
	global_load_lds_dwordx4 v[246:247], off
	v_lshl_add_u64 v[244:245], v[244:245], 0, v[250:251]
	v_lshl_add_u64 v[246:247], v[246:247], 0, v[250:251]
	s_sub_i32 m0, 0, s100
	s_max_i32 m0, m0, 0
	s_add_i32 m0, m0, s32
	s_add_i32 m0, m0, s32
	s_sub_i32 m0, m0, 0x10000
	s_nop 0
	global_load_lds_dwordx4 v[248:249], off
	s_add_i32 m0, m0, 896
	s_nop 0
	global_load_lds_dwordx4 v[248:249], off offset:128
	v_lshl_add_u64 v[248:249], v[248:249], 0, v[250:251]
	s_waitcnt lgkmcnt(0)
	s_nop 0
	v_mfma_f32_32x32x16_bf16 v[50:65], v[148:151], v[172:175], v[50:65]
	ds_read_b64_tr_b16 v[172:173], v185 offset:0x200
	ds_read_b64_tr_b16 v[174:175], v185 offset:0xa00
	v_mfma_f32_32x32x16_bf16 v[50:65], v[152:155], v[202:205], v[50:65]
	ds_read_b64_tr_b16 v[202:203], v185 offset:0x1200
	ds_read_b64_tr_b16 v[204:205], v185 offset:0x1a00
	v_mfma_f32_32x32x16_bf16 v[50:65], v[156:159], v[206:209], v[50:65]
	ds_read_b64_tr_b16 v[206:207], v185 offset:0x2200
	ds_read_b64_tr_b16 v[208:209], v185 offset:0x2a00
	v_mfma_f32_32x32x16_bf16 v[50:65], v[160:163], v[224:227], v[50:65]
	ds_read_b64_tr_b16 v[224:225], v185 offset:0x3200
	ds_read_b64_tr_b16 v[226:227], v185 offset:0x3a00
	s_waitcnt lgkmcnt(0)
	v_mfma_f32_32x32x16_bf16 v[34:49], v[148:151], v[172:175], v[34:49]
	ds_read_b64_tr_b16 v[172:173], v185 offset:0x400
	ds_read_b64_tr_b16 v[174:175], v185 offset:0xc00
	v_mfma_f32_32x32x16_bf16 v[34:49], v[152:155], v[202:205], v[34:49]
	ds_read_b64_tr_b16 v[202:203], v185 offset:0x1400
	ds_read_b64_tr_b16 v[204:205], v185 offset:0x1c00
	v_mfma_f32_32x32x16_bf16 v[34:49], v[156:159], v[206:209], v[34:49]
	ds_read_b64_tr_b16 v[206:207], v185 offset:0x2400
	ds_read_b64_tr_b16 v[208:209], v185 offset:0x2c00
	v_mfma_f32_32x32x16_bf16 v[34:49], v[160:163], v[224:227], v[34:49]
	ds_read_b64_tr_b16 v[224:225], v185 offset:0x3400
	ds_read_b64_tr_b16 v[226:227], v185 offset:0x3c00
	s_waitcnt lgkmcnt(0)
	v_mfma_f32_32x32x16_bf16 v[18:33], v[148:151], v[172:175], v[18:33]
	ds_read_b64_tr_b16 v[172:173], v185 offset:0x600
	ds_read_b64_tr_b16 v[174:175], v185 offset:0xe00
	v_mfma_f32_32x32x16_bf16 v[18:33], v[152:155], v[202:205], v[18:33]
	ds_read_b64_tr_b16 v[202:203], v185 offset:0x1600
	ds_read_b64_tr_b16 v[204:205], v185 offset:0x1e00
	v_mfma_f32_32x32x16_bf16 v[18:33], v[156:159], v[206:209], v[18:33]
	ds_read_b64_tr_b16 v[206:207], v185 offset:0x2600
	ds_read_b64_tr_b16 v[208:209], v185 offset:0x2e00
	v_mfma_f32_32x32x16_bf16 v[18:33], v[160:163], v[224:227], v[18:33]
	ds_read_b64_tr_b16 v[224:225], v185 offset:0x3600
	ds_read_b64_tr_b16 v[226:227], v185 offset:0x3e00
	s_waitcnt lgkmcnt(0)
	v_mfma_f32_32x32x16_bf16 v[2:17], v[148:151], v[172:175], v[2:17]
	s_cmp_le_i32 s7, s6
	v_mfma_f32_32x32x16_bf16 v[2:17], v[152:155], v[202:205], v[2:17]
	v_mfma_f32_32x32x16_bf16 v[2:17], v[156:159], v[206:209], v[2:17]
	v_mfma_f32_32x32x16_bf16 v[2:17], v[160:163], v[224:227], v[2:17]
	s_cbranch_scc1 .LBB0_91
; __device__ __forceinline__ void mask_tile(f32x16& p0, f32x16& p1, int dq, unsigned W) {
;     const float NEG = -__builtin_inff();
; #pragma unroll
;     for (int r = 0; r < 16; ++r) {
;         const int c = (r & 3) + 8 * (r >> 2);
;         if ((unsigned)(dq - c) >= W) p0[r] = NEG;
;         if ((unsigned)(dq - c - 32) >= W) p1[r] = NEG;
;     }
; }
; __device__ __forceinline__ void partialSM(f32x16& p0, f32x16& p1, float& m_reg, float& mn, float& alpha, bool rs) {
;     float pmax = p0[0]; for (int r = 1; r < 16; ++r) pmax = fmaxf(pmax, p0[r]); for (int r = 0; r < 16; ++r) pmax = fmaxf(pmax, p1[r]);
;     if (!rs) pmax = -__builtin_inff();
;     { auto rr = __builtin_amdgcn_permlane32_swap(__float_as_uint(pmax), __float_as_uint(pmax), false, false);
;       pmax = fmaxf(__uint_as_float(rr[0]), __uint_as_float(rr[1])); }
;     constexpr float C2 = 1.4426950408889634f * SCALE;
;     if (__builtin_expect(__all((pmax - m_reg) * SCALE <= THR), 1)) { mn = m_reg; alpha = 1.f; }
;     else { mn = fmaxf(m_reg, pmax); alpha = __builtin_amdgcn_exp2f((m_reg - mn) * C2); m_reg = mn; }
;     const float mnL = rs ? -mn * C2 : -__builtin_inff();
;     for (int r = 0; r < 16; ++r) p0[r] = fmaf(p0[r], C2, mnL); for (int r = 0; r < 16; ++r) p1[r] = fmaf(p1[r], C2, mnL);
;     for (int r = 0; r < 16; ++r) p0[r] = __builtin_amdgcn_exp2f(p0[r]);
; }
	v_add_u32_e32 v148, 0x4000007b, v197
	v_cmp_gt_u32_e32 vcc, 2.0, v148
	v_add_u32_e32 v148, 0x5b, v197
	s_nop 0
	v_cndmask_b32_e32 v82, v220, v82, vcc
	v_cmp_lt_u32_e32 vcc, s33, v148
	v_add_u32_e32 v148, 0x7a, v197
	s_nop 0
	v_cndmask_b32_e32 v66, v220, v66, vcc
	v_cmp_lt_u32_e32 vcc, s33, v148
	v_add_u32_e32 v148, 0x5a, v197
	s_nop 0
	v_cndmask_b32_e32 v83, v220, v83, vcc
	v_cmp_lt_u32_e32 vcc, s33, v148
	v_add_u32_e32 v148, 0x79, v197
	s_nop 0
	v_cndmask_b32_e32 v67, v220, v67, vcc
	v_cmp_lt_u32_e32 vcc, s33, v148
	v_add_u32_e32 v148, 0x59, v197
	s_nop 0
	v_cndmask_b32_e32 v84, v220, v84, vcc
	v_cmp_lt_u32_e32 vcc, s33, v148
	v_add_u32_e32 v148, 0x78, v197
	s_nop 0
	v_cndmask_b32_e32 v68, v220, v68, vcc
	v_cmp_lt_u32_e32 vcc, s33, v148
	v_add_u32_e32 v148, 0x58, v197
	s_nop 0
	v_cndmask_b32_e32 v85, v220, v85, vcc
	v_cmp_lt_u32_e32 vcc, s33, v148
	v_add_u32_e32 v148, 0x73, v197
	s_nop 0
	v_cndmask_b32_e32 v69, v220, v69, vcc
	v_cmp_lt_u32_e32 vcc, s33, v148
	v_add_u32_e32 v148, 0x53, v197
	s_nop 0
	v_cndmask_b32_e32 v86, v220, v86, vcc
	v_cmp_lt_u32_e32 vcc, s33, v148
	v_add_u32_e32 v148, 0x72, v197
	s_nop 0
	v_cndmask_b32_e32 v70, v220, v70, vcc
	v_cmp_lt_u32_e32 vcc, s33, v148
	v_add_u32_e32 v148, 0x52, v197
	s_nop 0
	v_cndmask_b32_e32 v87, v220, v87, vcc
	v_cmp_lt_u32_e32 vcc, s33, v148
	v_add_u32_e32 v148, 0x71, v197
	s_nop 0
	v_cndmask_b32_e32 v71, v220, v71, vcc
	v_cmp_lt_u32_e32 vcc, s33, v148
	v_add_u32_e32 v148, 0x51, v197
	s_nop 0
	v_cndmask_b32_e32 v88, v220, v88, vcc
	v_cmp_lt_u32_e32 vcc, s33, v148
	v_add_u32_e32 v148, 0x70, v197
	s_nop 0
	v_cndmask_b32_e32 v72, v220, v72, vcc
	v_cmp_lt_u32_e32 vcc, s33, v148
	v_add_u32_e32 v148, 0x50, v197
	s_nop 0
	v_cndmask_b32_e32 v89, v220, v89, vcc
	v_cmp_lt_u32_e32 vcc, s33, v148
	v_add_u32_e32 v148, 0x6b, v197
	s_nop 0
	v_cndmask_b32_e32 v73, v220, v73, vcc
	v_cmp_lt_u32_e32 vcc, s33, v148
	v_add_u32_e32 v148, 0x4b, v197
	s_nop 0
	v_cndmask_b32_e32 v90, v220, v90, vcc
	v_cmp_lt_u32_e32 vcc, s33, v148
	v_add_u32_e32 v148, 0x6a, v197
	s_nop 0
	v_cndmask_b32_e32 v74, v220, v74, vcc
	v_cmp_lt_u32_e32 vcc, s33, v148
	v_add_u32_e32 v148, 0x4a, v197
	s_nop 0
	v_cndmask_b32_e32 v91, v220, v91, vcc
	v_cmp_lt_u32_e32 vcc, s33, v148
	v_add_u32_e32 v148, 0x69, v197
	s_nop 0
	v_cndmask_b32_e32 v75, v220, v75, vcc
	v_cmp_lt_u32_e32 vcc, s33, v148
	v_add_u32_e32 v148, 0x49, v197
	s_nop 0
	v_cndmask_b32_e32 v92, v220, v92, vcc
	v_cmp_lt_u32_e32 vcc, s33, v148
	v_add_u32_e32 v148, 0x68, v197
	s_nop 0
	v_cndmask_b32_e32 v76, v220, v76, vcc
	v_cmp_lt_u32_e32 vcc, s33, v148
	v_add_u32_e32 v148, 0x48, v197
	s_nop 0
	v_cndmask_b32_e32 v93, v220, v93, vcc
	v_cmp_lt_u32_e32 vcc, s33, v148
	v_add_u32_e32 v148, 0x63, v197
	s_nop 0
	v_cndmask_b32_e32 v77, v220, v77, vcc
	v_cmp_lt_u32_e32 vcc, s33, v148
	v_add_u32_e32 v148, 0x43, v197
	s_nop 0
	v_cndmask_b32_e32 v94, v220, v94, vcc
	v_cmp_lt_u32_e32 vcc, s33, v148
	v_add_u32_e32 v148, 0x62, v197
	s_nop 0
	v_cndmask_b32_e32 v78, v220, v78, vcc
	v_cmp_lt_u32_e32 vcc, s33, v148
	v_add_u32_e32 v148, 0x42, v197
	s_nop 0
	v_cndmask_b32_e32 v95, v220, v95, vcc
	v_cmp_lt_u32_e32 vcc, s33, v148
	v_add_u32_e32 v148, 0x61, v197
	s_nop 0
	v_cndmask_b32_e32 v79, v220, v79, vcc
	v_cmp_lt_u32_e32 vcc, s33, v148
	v_add_u32_e32 v148, 0x41, v197
	s_nop 0
	v_cndmask_b32_e32 v96, v220, v96, vcc
	v_cmp_lt_u32_e32 vcc, s33, v148
	v_add_u32_e32 v148, 0x60, v197
	s_nop 0
	v_cndmask_b32_e32 v80, v220, v80, vcc
	v_cmp_lt_u32_e32 vcc, s33, v148
	v_add_u32_e32 v148, 64, v197
	s_nop 0
	v_cndmask_b32_e32 v97, v220, v97, vcc
	v_cmp_lt_u32_e32 vcc, s33, v148
	s_nop 1
	v_cndmask_b32_e32 v81, v220, v81, vcc
.LBB0_91:
	s_add_i32 s0, s3, -2
	s_lshr_b32 s8, s0, 2
	s_cmp_ge_i32 s8, s44
	s_cselect_b64 s[0:1], -1, 0
	s_lshl_b32 s8, 1, s8
	v_and_b32_e32 v148, s8, v165
	v_cmp_ne_u32_e32 vcc, 0, v148
	v_max_f32_e32 v148, v83, v83
	v_max_f32_e32 v149, v82, v82
	v_max_f32_e32 v148, v149, v148
	v_max3_f32 v148, v148, v84, v85
	v_max3_f32 v148, v148, v86, v87
	v_max3_f32 v148, v148, v88, v89
	v_max3_f32 v148, v148, v90, v91
	v_max3_f32 v148, v148, v92, v93
	v_max3_f32 v148, v148, v94, v95
	v_max3_f32 v148, v148, v96, v97
	v_max3_f32 v148, v148, v66, v67
	v_max3_f32 v148, v148, v68, v69
	v_max3_f32 v148, v148, v70, v71
	v_max3_f32 v148, v148, v72, v73
	v_max3_f32 v148, v148, v74, v75
	v_max3_f32 v148, v148, v76, v77
	v_max3_f32 v148, v148, v78, v79
	s_or_b64 s[40:41], s[0:1], vcc
	v_max3_f32 v148, v148, v80, v81
	v_cndmask_b32_e64 v148, v220, v148, s[40:41]
	v_mov_b32_e32 v149, v148
	s_nop 1
	v_permlane32_swap_b32_e32 v148, v149
	v_max_f32_e32 v149, v149, v149
	v_max_f32_e32 v148, v148, v148
	v_max_f32_e32 v148, v148, v149
	v_sub_f32_e32 v149, v148, v198
	v_mul_f32_e32 v149, 0x3db504f3, v149
	v_cmp_ge_f32_e32 vcc, s91, v149
	v_max_f32_e32 v149, v198, v198
	v_max_f32_e32 v148, v149, v148
	v_sub_f32_e32 v149, v198, v148
	v_mul_f32_e32 v149, 0x3e0293ee, v149
	v_exp_f32_e32 v149, v149
	s_cmp_eq_u64 vcc, exec
	s_cselect_b64 s[42:43], -1, 0
	v_cndmask_b32_e64 v202, v149, 1.0, s[42:43]
	v_cmp_gt_f32_e32 vcc, 1.0, v202
	s_cbranch_vccz .LBB0_95
	s_and_saveexec_b64 s[0:1], s[38:39]
	ds_write_b32 v187, v202 offset:128
	s_or_b64 exec, exec, s[0:1]
	s_waitcnt lgkmcnt(0)
	ds_read_b128 v[150:153], v186 offset:224
	ds_read_b128 v[154:157], v186 offset:192
	ds_read_b128 v[158:161], v186 offset:160
	ds_read_b128 v[172:175], v186 offset:128
	s_waitcnt lgkmcnt(3)
	v_pk_mul_f32 v[64:65], v[64:65], v[152:153]
	s_waitcnt lgkmcnt(2)
	v_pk_mul_f32 v[60:61], v[60:61], v[156:157]
	s_waitcnt lgkmcnt(1)
	v_pk_mul_f32 v[56:57], v[56:57], v[160:161]
	s_waitcnt lgkmcnt(0)
	v_pk_mul_f32 v[52:53], v[52:53], v[174:175]
	v_pk_mul_f32 v[62:63], v[62:63], v[150:151]
	v_pk_mul_f32 v[58:59], v[58:59], v[154:155]
	v_pk_mul_f32 v[54:55], v[54:55], v[158:159]
	v_pk_mul_f32 v[50:51], v[50:51], v[172:173]
	v_pk_mul_f32 v[48:49], v[48:49], v[152:153]
	v_pk_mul_f32 v[44:45], v[44:45], v[156:157]
	v_pk_mul_f32 v[40:41], v[40:41], v[160:161]
	v_pk_mul_f32 v[36:37], v[36:37], v[174:175]
	v_pk_mul_f32 v[46:47], v[46:47], v[150:151]
	v_pk_mul_f32 v[42:43], v[42:43], v[154:155]
	v_pk_mul_f32 v[38:39], v[38:39], v[158:159]
	v_pk_mul_f32 v[34:35], v[34:35], v[172:173]
	v_pk_mul_f32 v[32:33], v[32:33], v[152:153]
	v_pk_mul_f32 v[28:29], v[28:29], v[156:157]
	v_pk_mul_f32 v[24:25], v[24:25], v[160:161]
	v_pk_mul_f32 v[20:21], v[20:21], v[174:175]
	v_pk_mul_f32 v[30:31], v[30:31], v[150:151]
	v_pk_mul_f32 v[26:27], v[26:27], v[154:155]
	v_pk_mul_f32 v[22:23], v[22:23], v[158:159]
	v_pk_mul_f32 v[18:19], v[18:19], v[172:173]
	v_pk_mul_f32 v[16:17], v[16:17], v[152:153]
	v_pk_mul_f32 v[12:13], v[12:13], v[156:157]
	v_pk_mul_f32 v[8:9], v[8:9], v[160:161]
	v_pk_mul_f32 v[4:5], v[4:5], v[174:175]
	v_pk_mul_f32 v[14:15], v[14:15], v[150:151]
	v_pk_mul_f32 v[10:11], v[10:11], v[154:155]
	v_pk_mul_f32 v[6:7], v[6:7], v[158:159]
	v_pk_mul_f32 v[2:3], v[2:3], v[172:173]
; __device__ __forceinline__ void partialSM(f32x16& p0, f32x16& p1, float& m_reg, float& mn, float& alpha, bool rs) {
;     ...
;     constexpr float C2 = 1.4426950408889634f * SCALE;
;     if (__builtin_expect(__all((pmax - m_reg) * SCALE <= THR), 1)) { mn = m_reg; alpha = 1.f; }
;     else { mn = fmaxf(m_reg, pmax); alpha = __builtin_amdgcn_exp2f((m_reg - mn) * C2); m_reg = mn; }
;     const float mnL = rs ? -mn * C2 : -__builtin_inff();
;     for (int r = 0; r < 16; ++r) p0[r] = fmaf(p0[r], C2, mnL); for (int r = 0; r < 16; ++r) p1[r] = fmaf(p1[r], C2, mnL);
;     for (int r = 0; r < 16; ++r) p0[r] = __builtin_amdgcn_exp2f(p0[r]);
; }
; template <int KB>
; __device__ __forceinline__ void qkt(f32x16& p0, f32x16& p1, const char* K_lds, int r32, int hi, const bf16x8* qr) {
;     p0 = f32x16{}; p1 = f32x16{};
;     const char* kb[4];
; #pragma unroll
;     for (int dd = 0; dd < 4; ++dd) kb[dd] = K_lds + KB * SHM_K + KSWZ(r32, (dd * 16 + hi * 8) * 2);
; #pragma unroll
;     for (int d0 = 0; d0 < 8; ++d0) { const char* a = kb[d0 & 3] + (d0 >> 2) * 128;
;         bf16x8 b0 = *reinterpret_cast<const bf16x8*>(a);
;         bf16x8 b1 = *reinterpret_cast<const bf16x8*>(a + 32 * 256);
;         p0 = __builtin_amdgcn_mfma_f32_32x32x16_bf16(b0, qr[d0], p0, 0, 0, 0);
;         p1 = __builtin_amdgcn_mfma_f32_32x32x16_bf16(b1, qr[d0], p1, 0, 0, 0); }
; }
.LBB0_95:
	v_cndmask_b32_e64 v179, v148, v198, s[42:43]
	v_mul_f32_e32 v148, 0xbe0293ee, v179
	v_cndmask_b32_e64 v180, v220, v148, s[40:41]
	v_fmamk_f32 v82, v82, 0x3e0293ee, v180
	v_fmamk_f32 v83, v83, 0x3e0293ee, v180
	v_fmamk_f32 v84, v84, 0x3e0293ee, v180
	v_fmamk_f32 v85, v85, 0x3e0293ee, v180
	v_fmamk_f32 v86, v86, 0x3e0293ee, v180
	v_fmamk_f32 v87, v87, 0x3e0293ee, v180
	v_fmamk_f32 v88, v88, 0x3e0293ee, v180
	v_fmamk_f32 v89, v89, 0x3e0293ee, v180
	v_fmamk_f32 v90, v90, 0x3e0293ee, v180
	v_fmamk_f32 v91, v91, 0x3e0293ee, v180
	v_fmamk_f32 v92, v92, 0x3e0293ee, v180
	v_fmamk_f32 v93, v93, 0x3e0293ee, v180
	v_fmamk_f32 v94, v94, 0x3e0293ee, v180
	v_fmamk_f32 v95, v95, 0x3e0293ee, v180
	v_fmamk_f32 v96, v96, 0x3e0293ee, v180
	v_fmamk_f32 v97, v97, 0x3e0293ee, v180
	v_exp_f32_e32 v148, v82
	v_exp_f32_e32 v163, v83
	v_exp_f32_e32 v149, v84
	v_exp_f32_e32 v162, v85
	v_exp_f32_e32 v150, v86
	v_exp_f32_e32 v161, v87
	v_exp_f32_e32 v151, v88
	v_exp_f32_e32 v160, v89
	v_exp_f32_e32 v152, v90
	v_exp_f32_e32 v159, v91
	v_exp_f32_e32 v153, v92
	v_exp_f32_e32 v158, v93
	v_exp_f32_e32 v154, v94
	v_exp_f32_e32 v157, v95
	v_exp_f32_e32 v155, v96
	v_exp_f32_e32 v156, v97
	v_fmamk_f32 v203, v73, 0x3e0293ee, v180
	v_fmamk_f32 v204, v74, 0x3e0293ee, v180
	v_fmamk_f32 v208, v66, 0x3e0293ee, v180
	v_fmamk_f32 v209, v67, 0x3e0293ee, v180
	v_fmamk_f32 v223, v68, 0x3e0293ee, v180
	v_fmamk_f32 v224, v69, 0x3e0293ee, v180
	v_fmamk_f32 v225, v70, 0x3e0293ee, v180
	v_fmamk_f32 v198, v71, 0x3e0293ee, v180
	v_fmamk_f32 v201, v72, 0x3e0293ee, v180
	v_fmamk_f32 v205, v75, 0x3e0293ee, v180
	v_fmamk_f32 v206, v76, 0x3e0293ee, v180
	v_fmamk_f32 v207, v77, 0x3e0293ee, v180
	v_fmamk_f32 v181, v78, 0x3e0293ee, v180
	v_fmamk_f32 v226, v79, 0x3e0293ee, v180
	v_fmamk_f32 v227, v80, 0x3e0293ee, v180
	v_fmac_f32_e32 v180, 0x3e0293ee, v81
	s_waitcnt lgkmcnt(0)
	ds_read_b128 v[66:69], v169 offset:32768
	ds_read_b128 v[70:73], v169 offset:40960
	ds_read_b128 v[172:175], v193 offset:32768
	ds_read_b128 v[228:231], v193 offset:40960
	v_exp_f32_e32 v198, v198
	v_exp_f32_e32 v201, v201
	v_exp_f32_e32 v214, v204
	v_exp_f32_e32 v205, v205
	v_exp_f32_e32 v206, v206
	v_exp_f32_e32 v207, v207
	v_exp_f32_e32 v181, v181
	v_exp_f32_e32 v215, v226
	v_exp_f32_e32 v216, v227
	v_exp_f32_e32 v180, v180
	v_exp_f32_e32 v218, v209
	v_exp_f32_e32 v209, v203
	v_add_f32_e32 v203, 0, v148
	v_add_f32_e32 v203, v163, v203
	v_add_f32_e32 v203, v149, v203
	v_add_f32_e32 v203, v162, v203
	v_add_f32_e32 v203, v150, v203
	v_add_f32_e32 v203, v161, v203
	v_add_f32_e32 v203, v151, v203
	v_add_f32_e32 v203, v160, v203
	s_waitcnt lgkmcnt(3)
	v_mfma_f32_32x32x16_bf16 v[82:97], v[66:69], v[132:135], 0
	v_add_f32_e32 v203, v152, v203
	v_add_f32_e32 v203, v159, v203
	v_add_f32_e32 v203, v153, v203
	v_add_f32_e32 v203, v158, v203
	s_waitcnt lgkmcnt(2)
	v_mfma_f32_32x32x16_bf16 v[66:81], v[70:73], v[132:135], 0
	v_exp_f32_e32 v217, v208
	v_add_f32_e32 v203, v154, v203
	v_add_f32_e32 v203, v157, v203
	v_exp_f32_e32 v219, v223
	s_waitcnt lgkmcnt(1)
	v_mfma_f32_32x32x16_bf16 v[82:97], v[172:175], v[128:131], v[82:97]
	v_add_f32_e32 v203, v155, v203
	v_exp_f32_e32 v222, v224
	v_add_f32_e32 v203, v156, v203
	v_exp_f32_e32 v208, v225
	s_waitcnt lgkmcnt(0)
	v_mfma_f32_32x32x16_bf16 v[66:81], v[228:231], v[128:131], v[66:81]
	v_add_f32_e32 v203, v217, v203
	v_add_f32_e32 v203, v218, v203
	v_add_f32_e32 v203, v219, v203
	v_add_f32_e32 v203, v222, v203
	ds_read_b128 v[172:175], v194 offset:32768
	ds_read_b128 v[228:231], v194 offset:40960
	s_waitcnt lgkmcnt(1)
	v_mfma_f32_32x32x16_bf16 v[82:97], v[172:175], v[124:127], v[82:97]
	v_add_f32_e32 v203, v208, v203
	v_add_f32_e32 v203, v198, v203
	v_add_f32_e32 v203, v201, v203
	v_add_f32_e32 v203, v209, v203
	s_waitcnt lgkmcnt(0)
	v_mfma_f32_32x32x16_bf16 v[66:81], v[228:231], v[124:127], v[66:81]
	v_add_f32_e32 v203, v214, v203
	v_add_f32_e32 v203, v205, v203
	v_add_f32_e32 v203, v206, v203
	v_add_f32_e32 v203, v207, v203
	ds_read_b128 v[172:175], v195 offset:32768
	ds_read_b128 v[228:231], v195 offset:40960
	s_waitcnt lgkmcnt(1)
	v_mfma_f32_32x32x16_bf16 v[82:97], v[172:175], v[120:123], v[82:97]
	v_add_f32_e32 v203, v181, v203
	v_add_f32_e32 v203, v215, v203
	v_add_f32_e32 v203, v216, v203
	v_add_f32_e32 v203, v180, v203
	s_waitcnt lgkmcnt(0)
	v_mfma_f32_32x32x16_bf16 v[66:81], v[228:231], v[120:123], v[66:81]
	v_mov_b32_e32 v204, v203
	v_cvt_pk_bf16_f32 v148, v148, v163
	v_cvt_pk_bf16_f32 v149, v149, v162
	v_cvt_pk_bf16_f32 v150, v150, v161
	ds_read_b128 v[172:175], v169 offset:32896
	ds_read_b128 v[228:231], v169 offset:41088
	s_waitcnt lgkmcnt(1)
	v_mfma_f32_32x32x16_bf16 v[82:97], v[172:175], v[116:119], v[82:97]
	v_cvt_pk_bf16_f32 v151, v151, v160
	v_cvt_pk_bf16_f32 v152, v152, v159
	v_cvt_pk_bf16_f32 v153, v153, v158
	v_cvt_pk_bf16_f32 v154, v154, v157
	s_waitcnt lgkmcnt(0)
	v_mfma_f32_32x32x16_bf16 v[66:81], v[228:231], v[116:119], v[66:81]
	v_cvt_pk_bf16_f32 v155, v155, v156
	v_cvt_pk_bf16_f32 v156, v217, v218
	v_cvt_pk_bf16_f32 v157, v219, v222
	ds_read_b128 v[172:175], v193 offset:32896
	ds_read_b128 v[228:231], v193 offset:41088
	s_waitcnt lgkmcnt(1)
	v_mfma_f32_32x32x16_bf16 v[82:97], v[172:175], v[112:115], v[82:97]
	v_cvt_pk_bf16_f32 v158, v208, v198
	v_cvt_pk_bf16_f32 v159, v201, v209
	v_cvt_pk_bf16_f32 v160, v214, v205
	s_waitcnt lgkmcnt(0)
	v_mfma_f32_32x32x16_bf16 v[66:81], v[228:231], v[112:115], v[66:81]
	v_cvt_pk_bf16_f32 v161, v206, v207
	v_cvt_pk_bf16_f32 v162, v181, v215
	v_cvt_pk_bf16_f32 v163, v216, v180
	ds_read_b128 v[172:175], v194 offset:32896
	ds_read_b128 v[228:231], v194 offset:41088
	s_waitcnt lgkmcnt(1)
; __device__ __forceinline__ void finishSM(f32x16& p0, f32x16& p1, float alpha, float& l_reg, bf16x8& pa0, bf16x8& pa1, bf16x8& pa2, bf16x8& pa3) {
;     for (int r = 0; r < 16; ++r) p1[r] = __builtin_amdgcn_exp2f(p1[r]);
;     float ps = 0; for (int r = 0; r < 16; ++r) ps += p0[r]; for (int r = 0; r < 16; ++r) ps += p1[r];
;     { auto rr = __builtin_amdgcn_permlane32_swap(__float_as_uint(ps), __float_as_uint(ps), false, false);
;       ps = __uint_as_float(rr[0]) + __uint_as_float(rr[1]); }
;     l_reg = l_reg * alpha + ps;
;     ...
;     PK4(p0, 0, pa0); PK4(p0, 8, pa1); PK4(p1, 0, pa2); PK4(p1, 8, pa3);
;     ...
; }
; template <int KB>
; __device__ __forceinline__ void qkt(f32x16& p0, f32x16& p1, const char* K_lds, int r32, int hi, const bf16x8* qr) {
;     p0 = f32x16{}; p1 = f32x16{};
;     const char* kb[4];
; #pragma unroll
;     for (int dd = 0; dd < 4; ++dd) kb[dd] = K_lds + KB * SHM_K + KSWZ(r32, (dd * 16 + hi * 8) * 2);
; #pragma unroll
;     for (int d0 = 0; d0 < 8; ++d0) { const char* a = kb[d0 & 3] + (d0 >> 2) * 128;
;         bf16x8 b0 = *reinterpret_cast<const bf16x8*>(a);
;         bf16x8 b1 = *reinterpret_cast<const bf16x8*>(a + 32 * 256);
;         p0 = __builtin_amdgcn_mfma_f32_32x32x16_bf16(b0, qr[d0], p0, 0, 0, 0);
;         p1 = __builtin_amdgcn_mfma_f32_32x32x16_bf16(b1, qr[d0], p1, 0, 0, 0); }
; }
	v_mfma_f32_32x32x16_bf16 v[82:97], v[172:175], v[108:111], v[82:97]
	s_nop 1
	v_permlane32_swap_b32_e32 v203, v204
	v_permlane32_swap_b32_e32 v148, v150
	v_permlane32_swap_b32_e32 v149, v151
	s_waitcnt lgkmcnt(0)
	v_mfma_f32_32x32x16_bf16 v[66:81], v[228:231], v[108:111], v[66:81]
	v_permlane32_swap_b32_e32 v152, v154
	v_permlane32_swap_b32_e32 v153, v155
	v_permlane32_swap_b32_e32 v156, v158
	ds_read_b128 v[172:175], v195 offset:32896
	ds_read_b128 v[228:231], v195 offset:41088
	ds_read_b64_tr_b16 v[206:207], v185 offset:0x5000
	ds_read_b64_tr_b16 v[208:209], v185 offset:0x5800
	ds_read_b64_tr_b16 v[224:225], v185 offset:0x6000
	ds_read_b64_tr_b16 v[226:227], v185 offset:0x6800
	s_waitcnt lgkmcnt(5)
	v_mfma_f32_32x32x16_bf16 v[82:97], v[172:175], v[104:107], v[82:97]
	v_permlane32_swap_b32_e32 v157, v159
	v_permlane32_swap_b32_e32 v160, v162
	v_permlane32_swap_b32_e32 v161, v163
	s_waitcnt lgkmcnt(4)
	v_mfma_f32_32x32x16_bf16 v[66:81], v[228:231], v[104:107], v[66:81]
	ds_read_b64_tr_b16 v[172:173], v185 offset:0x4000
	ds_read_b64_tr_b16 v[174:175], v185 offset:0x4800
	ds_read_b64_tr_b16 v[228:229], v185 offset:0x7000
	ds_read_b64_tr_b16 v[230:231], v185 offset:0x7800
	s_cmp_lt_u32 s3, s2
	s_cselect_b64 s[22:23], -1, 0
	s_cmp_ge_u32 s3, s2
	s_sub_i32 m0, 0, s100
	s_max_i32 m0, m0, 0
	s_add_i32 m0, m0, s32
	s_add_i32 m0, m0, s32
	s_sub_i32 m0, m0, 0xc000
	s_nop 0
	global_load_lds_dwordx4 v[248:249], off
	s_add_i32 m0, m0, 896
	s_nop 0
	global_load_lds_dwordx4 v[248:249], off offset:128
	v_lshl_add_u64 v[248:249], v[248:249], 0, v[250:251]
	s_add_i32 m0, s3, 1
	s_cmp_ge_u32 m0, s2
	s_cbranch_scc1 .LBB0_97
	s_max_i32 m0, s100, 0
	s_add_i32 m0, m0, s32
	s_nop 0
	global_load_lds_dwordx4 v[244:245], off
	s_add_i32 m0, m0, 0x2000
	s_nop 0
	global_load_lds_dwordx4 v[246:247], off
	v_lshl_add_u64 v[244:245], v[244:245], 0, v[250:251]
	v_lshl_add_u64 v[246:247], v[246:247], 0, v[250:251]
; __device__ __forceinline__ void mask_tile(f32x16& p0, f32x16& p1, int dq, unsigned W) {
;     const float NEG = -__builtin_inff();
; #pragma unroll
;     for (int r = 0; r < 16; ++r) {
;         const int c = (r & 3) + 8 * (r >> 2);
;         if ((unsigned)(dq - c) >= W) p0[r] = NEG;
;         if ((unsigned)(dq - c - 32) >= W) p1[r] = NEG;
;     }
; }
; template <int VB>
; __device__ __forceinline__ void pv_tile(f32x16* o, int vb0, bf16x8 pa0, bf16x8 pa1, bf16x8 pa2, bf16x8 pa3) {
;     ...
;     PV_D0(0); PV_D0(1); PV_D0(2); PV_D0(3);
;     ...
; }
.LBB0_97:
	s_waitcnt lgkmcnt(0)
	s_nop 0
	v_mfma_f32_32x32x16_bf16 v[50:65], v[148:151], v[172:175], v[50:65]
	ds_read_b64_tr_b16 v[172:173], v185 offset:0x4200
	ds_read_b64_tr_b16 v[174:175], v185 offset:0x4a00
	v_mfma_f32_32x32x16_bf16 v[50:65], v[152:155], v[206:209], v[50:65]
	ds_read_b64_tr_b16 v[206:207], v185 offset:0x5200
	ds_read_b64_tr_b16 v[208:209], v185 offset:0x5a00
	v_mfma_f32_32x32x16_bf16 v[50:65], v[156:159], v[224:227], v[50:65]
	ds_read_b64_tr_b16 v[224:225], v185 offset:0x6200
	ds_read_b64_tr_b16 v[226:227], v185 offset:0x6a00
	v_mfma_f32_32x32x16_bf16 v[50:65], v[160:163], v[228:231], v[50:65]
	ds_read_b64_tr_b16 v[228:229], v185 offset:0x7200
	ds_read_b64_tr_b16 v[230:231], v185 offset:0x7a00
	s_waitcnt lgkmcnt(0)
	v_mfma_f32_32x32x16_bf16 v[34:49], v[148:151], v[172:175], v[34:49]
	ds_read_b64_tr_b16 v[172:173], v185 offset:0x4400
	ds_read_b64_tr_b16 v[174:175], v185 offset:0x4c00
	v_mfma_f32_32x32x16_bf16 v[34:49], v[152:155], v[206:209], v[34:49]
	ds_read_b64_tr_b16 v[206:207], v185 offset:0x5400
	ds_read_b64_tr_b16 v[208:209], v185 offset:0x5c00
	v_mfma_f32_32x32x16_bf16 v[34:49], v[156:159], v[224:227], v[34:49]
	ds_read_b64_tr_b16 v[224:225], v185 offset:0x6400
	ds_read_b64_tr_b16 v[226:227], v185 offset:0x6c00
	v_mfma_f32_32x32x16_bf16 v[34:49], v[160:163], v[228:231], v[34:49]
	ds_read_b64_tr_b16 v[228:229], v185 offset:0x7400
	ds_read_b64_tr_b16 v[230:231], v185 offset:0x7c00
	s_waitcnt lgkmcnt(0)
	v_mfma_f32_32x32x16_bf16 v[18:33], v[148:151], v[172:175], v[18:33]
	ds_read_b64_tr_b16 v[172:173], v185 offset:0x4600
	ds_read_b64_tr_b16 v[174:175], v185 offset:0x4e00
	v_mfma_f32_32x32x16_bf16 v[18:33], v[152:155], v[206:209], v[18:33]
	ds_read_b64_tr_b16 v[206:207], v185 offset:0x5600
	ds_read_b64_tr_b16 v[208:209], v185 offset:0x5e00
	v_mfma_f32_32x32x16_bf16 v[18:33], v[156:159], v[224:227], v[18:33]
	ds_read_b64_tr_b16 v[224:225], v185 offset:0x6600
	ds_read_b64_tr_b16 v[226:227], v185 offset:0x6e00
	v_mfma_f32_32x32x16_bf16 v[18:33], v[160:163], v[228:231], v[18:33]
	ds_read_b64_tr_b16 v[228:229], v185 offset:0x7600
	ds_read_b64_tr_b16 v[230:231], v185 offset:0x7e00
	s_waitcnt lgkmcnt(0)
	v_mfma_f32_32x32x16_bf16 v[2:17], v[148:151], v[172:175], v[2:17]
	s_add_i32 s0, s7, 64
	s_cmp_le_i32 s0, s6
	v_mfma_f32_32x32x16_bf16 v[2:17], v[152:155], v[206:209], v[2:17]
	v_mfma_f32_32x32x16_bf16 v[2:17], v[156:159], v[224:227], v[2:17]
	v_mfma_f32_32x32x16_bf16 v[2:17], v[160:163], v[228:231], v[2:17]
	v_subrev_u32_e32 v185, s100, v185
	s_cbranch_scc1 .LBB0_99
	v_add_u32_e32 v148, 0x4000003b, v197
	v_cmp_gt_u32_e32 vcc, 2.0, v148
	v_add_u32_e32 v148, 27, v197
	s_nop 0
	v_cndmask_b32_e32 v82, v220, v82, vcc
	v_cmp_lt_u32_e32 vcc, s33, v148
	v_add_u32_e32 v148, 58, v197
	s_nop 0
	v_cndmask_b32_e32 v66, v220, v66, vcc
	v_cmp_lt_u32_e32 vcc, s33, v148
	v_add_u32_e32 v148, 26, v197
	s_nop 0
	v_cndmask_b32_e32 v83, v220, v83, vcc
	v_cmp_lt_u32_e32 vcc, s33, v148
	v_add_u32_e32 v148, 57, v197
	s_nop 0
	v_cndmask_b32_e32 v67, v220, v67, vcc
	v_cmp_lt_u32_e32 vcc, s33, v148
	v_add_u32_e32 v148, 25, v197
	s_nop 0
	v_cndmask_b32_e32 v84, v220, v84, vcc
	v_cmp_lt_u32_e32 vcc, s33, v148
	v_add_u32_e32 v148, 56, v197
	s_nop 0
	v_cndmask_b32_e32 v68, v220, v68, vcc
	v_cmp_lt_u32_e32 vcc, s33, v148
	v_add_u32_e32 v148, 24, v197
	s_nop 0
	v_cndmask_b32_e32 v85, v220, v85, vcc
	v_cmp_lt_u32_e32 vcc, s33, v148
	v_add_u32_e32 v148, 51, v197
	s_nop 0
	v_cndmask_b32_e32 v69, v220, v69, vcc
	v_cmp_lt_u32_e32 vcc, s33, v148
	v_add_u32_e32 v148, 19, v197
	s_nop 0
	v_cndmask_b32_e32 v86, v220, v86, vcc
	v_cmp_lt_u32_e32 vcc, s33, v148
	v_add_u32_e32 v148, 50, v197
	s_nop 0
	v_cndmask_b32_e32 v70, v220, v70, vcc
	v_cmp_lt_u32_e32 vcc, s33, v148
	v_add_u32_e32 v148, 18, v197
	s_nop 0
	v_cndmask_b32_e32 v87, v220, v87, vcc
	v_cmp_lt_u32_e32 vcc, s33, v148
	v_add_u32_e32 v148, 49, v197
	s_nop 0
	v_cndmask_b32_e32 v71, v220, v71, vcc
	v_cmp_lt_u32_e32 vcc, s33, v148
	v_add_u32_e32 v148, 17, v197
	s_nop 0
	v_cndmask_b32_e32 v88, v220, v88, vcc
	v_cmp_lt_u32_e32 vcc, s33, v148
	v_add_u32_e32 v148, 48, v197
	s_nop 0
	v_cndmask_b32_e32 v72, v220, v72, vcc
	v_cmp_lt_u32_e32 vcc, s33, v148
	v_add_u32_e32 v148, 16, v197
	s_nop 0
	v_cndmask_b32_e32 v89, v220, v89, vcc
	v_cmp_lt_u32_e32 vcc, s33, v148
	v_add_u32_e32 v148, 43, v197
	s_nop 0
	v_cndmask_b32_e32 v73, v220, v73, vcc
	v_cmp_lt_u32_e32 vcc, s33, v148
	v_add_u32_e32 v148, 11, v197
	s_nop 0
	v_cndmask_b32_e32 v90, v220, v90, vcc
	v_cmp_lt_u32_e32 vcc, s33, v148
	v_add_u32_e32 v148, 42, v197
	s_nop 0
	v_cndmask_b32_e32 v74, v220, v74, vcc
	v_cmp_lt_u32_e32 vcc, s33, v148
	v_add_u32_e32 v148, 10, v197
	s_nop 0
	v_cndmask_b32_e32 v91, v220, v91, vcc
	v_cmp_lt_u32_e32 vcc, s33, v148
	v_add_u32_e32 v148, 41, v197
	s_nop 0
	v_cndmask_b32_e32 v75, v220, v75, vcc
	v_cmp_lt_u32_e32 vcc, s33, v148
	v_add_u32_e32 v148, 9, v197
	s_nop 0
	v_cndmask_b32_e32 v92, v220, v92, vcc
	v_cmp_lt_u32_e32 vcc, s33, v148
	v_add_u32_e32 v148, 40, v197
	s_nop 0
	v_cndmask_b32_e32 v76, v220, v76, vcc
	v_cmp_lt_u32_e32 vcc, s33, v148
	v_add_u32_e32 v148, 8, v197
	s_nop 0
	v_cndmask_b32_e32 v93, v220, v93, vcc
	v_cmp_lt_u32_e32 vcc, s33, v148
	v_add_u32_e32 v148, 35, v197
	s_nop 0
	v_cndmask_b32_e32 v77, v220, v77, vcc
	v_cmp_lt_u32_e32 vcc, s33, v148
	v_add_u32_e32 v148, 3, v197
	s_nop 0
	v_cndmask_b32_e32 v94, v220, v94, vcc
	v_cmp_lt_u32_e32 vcc, s33, v148
	v_add_u32_e32 v148, 34, v197
	s_nop 0
	v_cndmask_b32_e32 v78, v220, v78, vcc
	v_cmp_lt_u32_e32 vcc, s33, v148
	v_add_u32_e32 v148, 2, v197
	s_nop 0
	v_cndmask_b32_e32 v95, v220, v95, vcc
	v_cmp_lt_u32_e32 vcc, s33, v148
	v_add_u32_e32 v148, 33, v197
	s_nop 0
	v_cndmask_b32_e32 v79, v220, v79, vcc
	v_cmp_lt_u32_e32 vcc, s33, v148
	v_add_u32_e32 v148, 1, v197
	s_nop 0
	v_cndmask_b32_e32 v96, v220, v96, vcc
	v_cmp_lt_u32_e32 vcc, s33, v148
	v_add_u32_e32 v148, 32, v197
	s_nop 0
	v_cndmask_b32_e32 v80, v220, v80, vcc
	v_cmp_lt_u32_e32 vcc, s33, v148
	s_nop 1
	v_cndmask_b32_e32 v97, v220, v97, vcc
	v_cmp_lt_u32_e32 vcc, s33, v197
	s_nop 1
	v_cndmask_b32_e32 v81, v220, v81, vcc

; __device__ __forceinline__ void partialSM(f32x16& p0, f32x16& p1, float& m_reg, float& mn, float& alpha, bool rs) {
;     ...
;     if (__builtin_expect(__all((pmax - m_reg) * SCALE <= THR), 1)) { mn = m_reg; alpha = 1.f; }
;     else { mn = fmaxf(m_reg, pmax); alpha = __builtin_amdgcn_exp2f((m_reg - mn) * C2); m_reg = mn; }
.LBB0_101:
	v_max_f32_e32 v100, v179, v179
	v_max_f32_e32 v100, v100, v148
	v_sub_f32_e32 v101, v179, v100
	v_mul_f32_e32 v101, 0x3e0293ee, v101
	v_exp_f32_e32 v101, v101
	s_nop 0
	v_cndmask_b32_e64 v201, v101, 1.0, s[42:43]
	v_cmp_gt_f32_e32 vcc, 1.0, v201
	s_cbranch_vccz .LBB0_105
	s_and_saveexec_b64 s[0:1], s[38:39]
	ds_write_b32 v187, v201 offset:128
	s_or_b64 exec, exec, s[0:1]
	s_waitcnt lgkmcnt(0)
	ds_read_b128 v[136:139], v186 offset:224
	ds_read_b128 v[140:143], v186 offset:192
	ds_read_b128 v[144:147], v186 offset:160
	ds_read_b128 v[148:151], v186 offset:128
	s_waitcnt lgkmcnt(3)
	v_pk_mul_f32 v[64:65], v[64:65], v[138:139]
	s_waitcnt lgkmcnt(2)
	v_pk_mul_f32 v[60:61], v[60:61], v[142:143]
	s_waitcnt lgkmcnt(1)
	v_pk_mul_f32 v[56:57], v[56:57], v[146:147]
	s_waitcnt lgkmcnt(0)
	v_pk_mul_f32 v[52:53], v[52:53], v[150:151]
	v_pk_mul_f32 v[62:63], v[62:63], v[136:137]
	v_pk_mul_f32 v[58:59], v[58:59], v[140:141]
	v_pk_mul_f32 v[54:55], v[54:55], v[144:145]
	v_pk_mul_f32 v[50:51], v[50:51], v[148:149]
	v_pk_mul_f32 v[48:49], v[48:49], v[138:139]
	v_pk_mul_f32 v[44:45], v[44:45], v[142:143]
	v_pk_mul_f32 v[40:41], v[40:41], v[146:147]
	v_pk_mul_f32 v[36:37], v[36:37], v[150:151]
	v_pk_mul_f32 v[46:47], v[46:47], v[136:137]
	v_pk_mul_f32 v[42:43], v[42:43], v[140:141]
	v_pk_mul_f32 v[38:39], v[38:39], v[144:145]
	v_pk_mul_f32 v[34:35], v[34:35], v[148:149]
	v_pk_mul_f32 v[32:33], v[32:33], v[138:139]
	v_pk_mul_f32 v[28:29], v[28:29], v[142:143]
	v_pk_mul_f32 v[24:25], v[24:25], v[146:147]
	v_pk_mul_f32 v[20:21], v[20:21], v[150:151]
	v_pk_mul_f32 v[30:31], v[30:31], v[136:137]
	v_pk_mul_f32 v[26:27], v[26:27], v[140:141]
	v_pk_mul_f32 v[22:23], v[22:23], v[144:145]
	v_pk_mul_f32 v[18:19], v[18:19], v[148:149]
	v_pk_mul_f32 v[16:17], v[16:17], v[138:139]
	v_pk_mul_f32 v[12:13], v[12:13], v[142:143]
	v_pk_mul_f32 v[8:9], v[8:9], v[146:147]
	v_pk_mul_f32 v[4:5], v[4:5], v[150:151]
	v_pk_mul_f32 v[14:15], v[14:15], v[136:137]
	v_pk_mul_f32 v[10:11], v[10:11], v[140:141]
	v_pk_mul_f32 v[6:7], v[6:7], v[144:145]
	v_pk_mul_f32 v[2:3], v[2:3], v[148:149]
